# adds: attention epilogue gate loads of the second query half hoisted next to the first half's (no longer queued behind the Y stores)
# baseline (speedup 1.0000x reference)
.LBB0_1619:
	s_or_b64 exec, exec, s[48:49]
	v_mov_b32_e32 v4, v222
	s_waitcnt lgkmcnt(0)
	v_mov_b32_e32 v40, v139
	v_lshlrev_b32_e32 v0, 3, v4
	v_and_b32_e32 v138, 0x78, v0
	v_ashrrev_i32_e32 v8, 4, v4
	v_lshlrev_b32_e32 v5, 2, v138
	v_ashrrev_i32_e32 v9, 31, v8
	global_load_dwordx4 v[0:3], v5, s[26:27]
	global_load_dwordx4 v[14:17], v5, s[26:27] offset:16
	v_mov_b32_e32 v5, v139
	v_lshlrev_b32_e32 v4, 1, v138
	v_lshl_add_u64 v[6:7], v[64:65], 0, v[8:9]
	v_lshl_add_u64 v[10:11], s[28:29], 0, v[4:5]
	v_lshlrev_b64 v[6:7], 12, v[6:7]
	v_lshl_add_u64 v[12:13], v[10:11], 0, v[6:7]
	global_load_dwordx4 v[18:21], v[12:13], off nt
	v_add_u32_e32 v12, 4, v8
	v_ashrrev_i32_e32 v13, 31, v12
	v_lshl_add_u64 v[22:23], v[64:65], 0, v[12:13]
	v_lshlrev_b64 v[38:39], 12, v[22:23]
	v_lshl_add_u64 v[22:23], v[10:11], 0, v[38:39]
	global_load_dwordx4 v[22:25], v[22:23], off nt
	v_add_u32_e32 v26, 8, v8
	v_add_u32_e32 v28, 12, v8
	v_ashrrev_i32_e32 v27, 31, v26
	v_ashrrev_i32_e32 v29, 31, v28
	v_add_u32_e32 v46, s56, v4
	v_lshl_add_u64 v[4:5], v[64:65], 0, v[26:27]
	v_lshl_add_u64 v[30:31], v[64:65], 0, v[28:29]
	v_lshl_add_u32 v29, v12, 8, v46
	v_lshlrev_b64 v[42:43], 12, v[4:5]
	v_lshlrev_b64 v[12:13], 12, v[30:31]
	v_lshl_add_u32 v9, v8, 8, v46
	v_lshl_add_u32 v47, v26, 8, v46
	v_lshl_add_u64 v[26:27], s[30:31], 0, v[6:7]
	v_lshl_add_u64 v[30:31], v[10:11], 0, v[42:43]
	v_lshl_add_u64 v[34:35], v[10:11], 0, v[12:13]
	v_lshl_add_u32 v48, v28, 8, v46
	ds_read_b128 v[4:7], v9
	v_lshl_add_u64 v[44:45], v[26:27], 0, v[138:139]
	ds_read_b128 v[26:29], v29
	global_load_dwordx4 v[30:33], v[30:31], off nt
	s_nop 0
	global_load_dwordx4 v[34:37], v[34:35], off nt
	v_add_u32_e32 v232, 16, v8
	v_ashrrev_i32_e32 v233, 31, v232
	v_lshl_add_u64 v[232:233], v[64:65], 0, v[232:233]
	v_lshlrev_b64 v[232:233], 12, v[232:233]
	v_lshl_add_u64 v[232:233], v[10:11], 0, v[232:233]
	global_load_dwordx4 v[236:239], v[232:233], off nt
	v_add_u32_e32 v232, 20, v8
	v_ashrrev_i32_e32 v233, 31, v232
	v_lshl_add_u64 v[232:233], v[64:65], 0, v[232:233]
	v_lshlrev_b64 v[232:233], 12, v[232:233]
	v_lshl_add_u64 v[232:233], v[10:11], 0, v[232:233]
	global_load_dwordx4 v[240:243], v[232:233], off nt
	v_add_u32_e32 v232, 24, v8
	v_ashrrev_i32_e32 v233, 31, v232
	v_lshl_add_u64 v[232:233], v[64:65], 0, v[232:233]
	v_lshlrev_b64 v[232:233], 12, v[232:233]
	v_lshl_add_u64 v[232:233], v[10:11], 0, v[232:233]
	global_load_dwordx4 v[244:247], v[232:233], off nt
	v_add_u32_e32 v232, 28, v8
	v_ashrrev_i32_e32 v233, 31, v232
	v_lshl_add_u64 v[232:233], v[64:65], 0, v[232:233]
	v_lshlrev_b64 v[232:233], 12, v[232:233]
	v_lshl_add_u64 v[232:233], v[10:11], 0, v[232:233]
	global_load_dwordx4 v[248:251], v[232:233], off nt
	v_mov_b32_e32 v41, v139
	s_waitcnt lgkmcnt(1)
	v_cvt_f32_f16_sdwa v49, v4 dst_sel:DWORD dst_unused:UNUSED_PAD src0_sel:WORD_1
	v_cvt_f32_f16_sdwa v51, v5 dst_sel:DWORD dst_unused:UNUSED_PAD src0_sel:WORD_1
	v_cvt_f32_f16_sdwa v53, v6 dst_sel:DWORD dst_unused:UNUSED_PAD src0_sel:WORD_1
	v_cvt_f32_f16_sdwa v55, v7 dst_sel:DWORD dst_unused:UNUSED_PAD src0_sel:WORD_1
	v_cvt_f32_f16_e32 v9, v4
	v_cvt_f32_f16_e32 v50, v5
	v_cvt_f32_f16_e32 v52, v6
	v_cvt_f32_f16_e32 v54, v7
	s_waitcnt lgkmcnt(0)
	v_cvt_f32_f16_e32 v56, v26
	v_cvt_f32_f16_sdwa v26, v26 dst_sel:DWORD dst_unused:UNUSED_PAD src0_sel:WORD_1
	v_lshl_add_u64 v[12:13], s[30:31], 0, v[12:13]
	v_lshl_add_u64 v[12:13], v[12:13], 0, v[138:139]
	s_mov_b64 s[48:49], 0
	s_and_b64 vcc, exec, s[0:1]
	s_waitcnt vmcnt(9)
	v_pk_mul_f32 v[4:5], v[2:3], s[16:17] op_sel_hi:[1,0]
	v_pk_mul_f32 v[6:7], v[0:1], s[16:17] op_sel_hi:[1,0]
	s_waitcnt vmcnt(8)
	v_pk_mul_f32 v[0:1], v[16:17], s[16:17] op_sel_hi:[1,0]
	v_pk_mul_f32 v[2:3], v[14:15], s[16:17] op_sel_hi:[1,0]
	v_mul_f32_e32 v14, v7, v49
	v_mul_f32_e32 v16, v5, v51
	v_mul_f32_e32 v49, v3, v53
	v_mul_f32_e32 v51, v1, v55
	s_waitcnt vmcnt(7)
	v_cvt_f32_f16_e32 v53, v18
	v_cvt_f32_f16_sdwa v18, v18 dst_sel:DWORD dst_unused:UNUSED_PAD src0_sel:WORD_1
	v_cvt_f32_f16_e32 v55, v20
	v_cvt_f32_f16_sdwa v20, v20 dst_sel:DWORD dst_unused:UNUSED_PAD src0_sel:WORD_1
	v_mul_f32_e32 v9, v6, v9
	v_mul_f32_e32 v17, v2, v52
	v_mul_f32_e32 v15, v4, v50
	v_mul_f32_e32 v50, v0, v54
	v_mul_f32_e32 v52, v6, v56
	v_cvt_f32_f16_e32 v54, v19
	v_cvt_f32_f16_sdwa v19, v19 dst_sel:DWORD dst_unused:UNUSED_PAD src0_sel:WORD_1
	v_cvt_f32_f16_e32 v56, v21
	v_cvt_f32_f16_sdwa v21, v21 dst_sel:DWORD dst_unused:UNUSED_PAD src0_sel:WORD_1
	v_mul_f32_e32 v9, v9, v53
	v_mul_f32_e32 v14, v14, v18
	v_mul_f32_e32 v17, v17, v55
	v_mul_f32_e32 v18, v49, v20
	v_med3_f32 v9, v9, s62, v187
	v_med3_f32 v14, v14, s62, v187
	v_med3_f32 v17, v17, s62, v187
	v_med3_f32 v18, v18, s62, v187
	v_cvt_pk_fp8_f32 v40, v9, v14
	v_cvt_pk_fp8_f32 v41, v17, v18
	v_mul_f32_e32 v15, v15, v54
	v_mul_f32_e32 v16, v16, v19
	v_mul_f32_e32 v19, v50, v56
	v_mul_f32_e32 v20, v51, v21
	v_med3_f32 v15, v15, s62, v187
	v_med3_f32 v16, v16, s62, v187
	v_med3_f32 v9, v19, s62, v187
	v_med3_f32 v14, v20, s62, v187
	v_cvt_pk_fp8_f32 v40, v15, v16 op_sel:[0,0,1]
	v_cvt_pk_fp8_f32 v41, v9, v14 op_sel:[0,0,1]
	s_waitcnt vmcnt(6)
	v_cvt_f32_f16_sdwa v14, v22 dst_sel:DWORD dst_unused:UNUSED_PAD src0_sel:WORD_1
	v_cvt_f32_f16_e32 v16, v27
	v_cvt_f32_f16_e32 v57, v22
	v_cvt_f32_f16_e32 v17, v23
	v_cvt_f32_f16_sdwa v18, v27 dst_sel:DWORD dst_unused:UNUSED_PAD src0_sel:WORD_1
	v_mul_f32_e32 v9, v7, v26
	v_mul_f32_e32 v9, v9, v14
	v_mul_f32_e32 v14, v4, v16
	v_mul_f32_e32 v15, v52, v57
	v_mul_f32_e32 v14, v14, v17
	v_cvt_f32_f16_sdwa v17, v23 dst_sel:DWORD dst_unused:UNUSED_PAD src0_sel:WORD_1
	v_mul_f32_e32 v16, v5, v18
	v_med3_f32 v15, v15, s62, v187
	v_med3_f32 v9, v9, s62, v187
	v_mov_b32_e32 v18, v139
	v_cvt_pk_fp8_f32 v18, v15, v9
	v_mul_f32_e32 v9, v16, v17
	v_med3_f32 v14, v14, s62, v187
	v_med3_f32 v9, v9, s62, v187
	v_cvt_pk_fp8_f32 v18, v14, v9 op_sel:[0,0,1]
	v_cvt_f32_f16_e32 v9, v28
	v_cvt_f32_f16_e32 v14, v24
	v_cvt_f32_f16_sdwa v15, v28 dst_sel:DWORD dst_unused:UNUSED_PAD src0_sel:WORD_1
	v_cvt_f32_f16_sdwa v16, v24 dst_sel:DWORD dst_unused:UNUSED_PAD src0_sel:WORD_1
	v_mul_f32_e32 v9, v2, v9
	v_mul_f32_e32 v9, v9, v14
	v_mul_f32_e32 v14, v3, v15
	v_cvt_f32_f16_e32 v15, v29
	v_mul_f32_e32 v14, v14, v16
	v_cvt_f32_f16_e32 v16, v25
	v_cvt_f32_f16_sdwa v17, v29 dst_sel:DWORD dst_unused:UNUSED_PAD src0_sel:WORD_1
	v_cvt_f32_f16_sdwa v19, v25 dst_sel:DWORD dst_unused:UNUSED_PAD src0_sel:WORD_1
	v_mul_f32_e32 v15, v0, v15
	v_mul_f32_e32 v15, v15, v16
	v_mul_f32_e32 v16, v1, v17
	v_mul_f32_e32 v20, v16, v19
	v_med3_f32 v9, v9, s62, v187
	v_med3_f32 v14, v14, s62, v187
	v_mov_b32_e32 v19, v139
	v_cvt_pk_fp8_f32 v19, v9, v14
	v_med3_f32 v9, v15, s62, v187
	ds_read_b128 v[14:17], v47
	v_med3_f32 v20, v20, s62, v187
	v_cvt_pk_fp8_f32 v19, v9, v20 op_sel:[0,0,1]
	v_lshl_add_u64 v[20:21], s[30:31], 0, v[38:39]
	v_lshl_add_u64 v[20:21], v[20:21], 0, v[138:139]
	s_waitcnt lgkmcnt(0)
	v_cvt_f32_f16_e32 v9, v14
	v_cvt_f32_f16_sdwa v14, v14 dst_sel:DWORD dst_unused:UNUSED_PAD src0_sel:WORD_1
	global_store_dwordx2 v[20:21], v[18:19], off offset:2048
	s_waitcnt vmcnt(6)
	v_cvt_f32_f16_sdwa v18, v30 dst_sel:DWORD dst_unused:UNUSED_PAD src0_sel:WORD_1
	v_cvt_f32_f16_e32 v19, v15
	v_cvt_f32_f16_e32 v22, v30
	v_cvt_f32_f16_e32 v20, v31
	v_mul_f32_e32 v14, v7, v14
	v_mul_f32_e32 v9, v6, v9
	v_cvt_f32_f16_sdwa v15, v15 dst_sel:DWORD dst_unused:UNUSED_PAD src0_sel:WORD_1
	v_mul_f32_e32 v14, v14, v18
	v_mul_f32_e32 v18, v4, v19
	v_mul_f32_e32 v9, v9, v22
	v_mul_f32_e32 v19, v18, v20
	v_cvt_f32_f16_sdwa v20, v31 dst_sel:DWORD dst_unused:UNUSED_PAD src0_sel:WORD_1
	v_med3_f32 v9, v9, s62, v187
	v_med3_f32 v14, v14, s62, v187
	v_mov_b32_e32 v18, v139
	v_cvt_pk_fp8_f32 v18, v9, v14
	v_mul_f32_e32 v15, v5, v15
	v_mul_f32_e32 v9, v15, v20
	v_med3_f32 v14, v19, s62, v187
	v_med3_f32 v9, v9, s62, v187
	v_cvt_pk_fp8_f32 v18, v14, v9 op_sel:[0,0,1]
	v_cvt_f32_f16_e32 v9, v16
	v_cvt_f32_f16_e32 v14, v32
	v_cvt_f32_f16_sdwa v15, v16 dst_sel:DWORD dst_unused:UNUSED_PAD src0_sel:WORD_1
	v_cvt_f32_f16_sdwa v16, v32 dst_sel:DWORD dst_unused:UNUSED_PAD src0_sel:WORD_1
	v_mul_f32_e32 v9, v2, v9
	v_mul_f32_e32 v9, v9, v14
	v_mul_f32_e32 v14, v3, v15
	v_cvt_f32_f16_e32 v15, v17
	v_mul_f32_e32 v14, v14, v16
	v_cvt_f32_f16_e32 v16, v33
	v_cvt_f32_f16_sdwa v17, v17 dst_sel:DWORD dst_unused:UNUSED_PAD src0_sel:WORD_1
	v_cvt_f32_f16_sdwa v19, v33 dst_sel:DWORD dst_unused:UNUSED_PAD src0_sel:WORD_1
	v_mul_f32_e32 v15, v0, v15
	v_mul_f32_e32 v15, v15, v16
	v_mul_f32_e32 v16, v1, v17
	v_mul_f32_e32 v20, v16, v19
	v_med3_f32 v9, v9, s62, v187
	v_med3_f32 v14, v14, s62, v187
	v_mov_b32_e32 v19, v139
	v_cvt_pk_fp8_f32 v19, v9, v14
	v_med3_f32 v9, v15, s62, v187
	ds_read_b128 v[14:17], v48
	v_med3_f32 v20, v20, s62, v187
	v_cvt_pk_fp8_f32 v19, v9, v20 op_sel:[0,0,1]
	s_waitcnt vmcnt(5)
	v_cvt_f32_f16_e32 v22, v34
	v_cvt_f32_f16_sdwa v23, v34 dst_sel:DWORD dst_unused:UNUSED_PAD src0_sel:WORD_1
	s_waitcnt lgkmcnt(0)
	v_cvt_f32_f16_e32 v9, v14
	v_cvt_f32_f16_sdwa v14, v14 dst_sel:DWORD dst_unused:UNUSED_PAD src0_sel:WORD_1
	v_cvt_f32_f16_sdwa v24, v35 dst_sel:DWORD dst_unused:UNUSED_PAD src0_sel:WORD_1
	v_lshl_add_u64 v[20:21], s[30:31], 0, v[42:43]
	v_mul_f32_e32 v9, v6, v9
	v_mul_f32_e32 v9, v9, v22
	v_mul_f32_e32 v14, v7, v14
	v_cvt_f32_f16_e32 v22, v15
	v_mul_f32_e32 v14, v14, v23
	v_cvt_f32_f16_e32 v23, v35
	v_cvt_f32_f16_sdwa v15, v15 dst_sel:DWORD dst_unused:UNUSED_PAD src0_sel:WORD_1
	v_mul_f32_e32 v22, v4, v22
	v_med3_f32 v9, v9, s62, v187
	v_mul_f32_e32 v22, v22, v23
	v_med3_f32 v23, v14, s62, v187
	v_mov_b32_e32 v14, v139
	v_cvt_pk_fp8_f32 v14, v9, v23
	v_med3_f32 v9, v22, s62, v187
	v_cvt_f32_f16_e32 v22, v16
	v_cvt_f32_f16_sdwa v16, v16 dst_sel:DWORD dst_unused:UNUSED_PAD src0_sel:WORD_1
	v_mul_f32_e32 v15, v5, v15
	v_cvt_f32_f16_e32 v23, v36
	v_mul_f32_e32 v15, v15, v24
	v_med3_f32 v15, v15, s62, v187
	v_cvt_pk_fp8_f32 v14, v9, v15 op_sel:[0,0,1]
	v_mul_f32_e32 v9, v2, v22
	v_mul_f32_e32 v15, v3, v16
	v_cvt_f32_f16_sdwa v16, v36 dst_sel:DWORD dst_unused:UNUSED_PAD src0_sel:WORD_1
	v_cvt_f32_f16_e32 v22, v17
	v_mul_f32_e32 v9, v9, v23
	v_cvt_f32_f16_e32 v23, v37
	v_cvt_f32_f16_sdwa v17, v17 dst_sel:DWORD dst_unused:UNUSED_PAD src0_sel:WORD_1
	v_mul_f32_e32 v15, v15, v16
	v_mul_f32_e32 v16, v0, v22
	v_cvt_f32_f16_sdwa v22, v37 dst_sel:DWORD dst_unused:UNUSED_PAD src0_sel:WORD_1
	v_mul_f32_e32 v16, v16, v23
	v_med3_f32 v9, v9, s62, v187
	v_med3_f32 v23, v15, s62, v187
	v_mov_b32_e32 v15, v139
	v_cvt_pk_fp8_f32 v15, v9, v23
	v_mul_f32_e32 v17, v1, v17
	v_mul_f32_e32 v9, v17, v22
	v_med3_f32 v16, v16, s62, v187
	v_med3_f32 v9, v9, s62, v187
	v_cvt_pk_fp8_f32 v15, v16, v9 op_sel:[0,0,1]
	v_lshl_add_u64 v[20:21], v[20:21], 0, v[138:139]
	global_store_dwordx2 v[20:21], v[18:19], off offset:2048
	v_add_u32_e32 v20, 16, v8
	v_ashrrev_i32_e32 v21, 31, v20
	global_store_dwordx2 v[12:13], v[14:15], off offset:2048
	v_lshl_add_u64 v[12:13], v[64:65], 0, v[20:21]
	global_store_dwordx2 v[44:45], v[40:41], off offset:2048
	v_lshlrev_b64 v[24:25], 12, v[12:13]
	v_lshl_add_u64 v[12:13], v[10:11], 0, v[24:25]
	v_add_u32_e32 v22, 20, v8
	v_ashrrev_i32_e32 v23, 31, v22
	v_lshl_add_u64 v[16:17], v[64:65], 0, v[22:23]
	v_lshlrev_b64 v[28:29], 12, v[16:17]
	v_lshl_add_u64 v[16:17], v[10:11], 0, v[28:29]
	v_lshl_add_u32 v9, v20, 8, v46
	v_add_u32_e32 v20, 24, v8
	v_ashrrev_i32_e32 v21, 31, v20
	v_lshl_add_u32 v36, v22, 8, v46
	v_lshl_add_u64 v[22:23], v[64:65], 0, v[20:21]
	v_lshlrev_b64 v[30:31], 12, v[22:23]
	v_lshl_add_u32 v37, v20, 8, v46
	ds_read_b128 v[20:23], v9
	v_add_u32_e32 v32, 28, v8
	v_ashrrev_i32_e32 v33, 31, v32
	v_lshl_add_u64 v[8:9], v[64:65], 0, v[32:33]
	v_lshlrev_b64 v[8:9], 12, v[8:9]
	v_lshl_add_u64 v[26:27], v[10:11], 0, v[30:31]
	v_lshl_add_u64 v[34:35], v[10:11], 0, v[8:9]
	s_waitcnt lgkmcnt(0)
	v_cvt_f32_f16_e32 v10, v20
	v_cvt_f32_f16_sdwa v20, v20 dst_sel:DWORD dst_unused:UNUSED_PAD src0_sel:WORD_1
	v_lshl_add_u32 v38, v32, 8, v46
	v_mov_b32_e32 v32, v139
	v_mul_f32_e32 v10, v6, v10
	v_mov_b32_e32 v33, v139
	s_waitcnt vmcnt(7)
	v_mov_b32_e32 v12, v236
	v_mov_b32_e32 v13, v237
	v_mov_b32_e32 v14, v238
	v_mov_b32_e32 v15, v239
	v_cvt_f32_f16_e32 v11, v12
	v_cvt_f32_f16_sdwa v12, v12 dst_sel:DWORD dst_unused:UNUSED_PAD src0_sel:WORD_1
	v_mul_f32_e32 v10, v10, v11
	v_mul_f32_e32 v11, v7, v20
	v_mul_f32_e32 v11, v11, v12
	v_cvt_f32_f16_e32 v12, v21
	v_cvt_f32_f16_e32 v20, v13
	v_cvt_f32_f16_sdwa v21, v21 dst_sel:DWORD dst_unused:UNUSED_PAD src0_sel:WORD_1
	v_cvt_f32_f16_sdwa v13, v13 dst_sel:DWORD dst_unused:UNUSED_PAD src0_sel:WORD_1
	v_mul_f32_e32 v12, v4, v12
	v_mul_f32_e32 v12, v12, v20
	v_mul_f32_e32 v20, v5, v21
	v_mul_f32_e32 v13, v20, v13
	v_med3_f32 v10, v10, s62, v187
	v_med3_f32 v11, v11, s62, v187
	v_cvt_pk_fp8_f32 v32, v10, v11
	v_med3_f32 v20, v12, s62, v187
	v_med3_f32 v21, v13, s62, v187
	v_cvt_pk_fp8_f32 v32, v20, v21 op_sel:[0,0,1]
	v_cvt_f32_f16_e32 v20, v22
	v_cvt_f32_f16_e32 v21, v14
	v_cvt_f32_f16_sdwa v22, v22 dst_sel:DWORD dst_unused:UNUSED_PAD src0_sel:WORD_1
	v_cvt_f32_f16_sdwa v14, v14 dst_sel:DWORD dst_unused:UNUSED_PAD src0_sel:WORD_1
	v_mul_f32_e32 v20, v2, v20
	v_mul_f32_e32 v20, v20, v21
	v_mul_f32_e32 v21, v3, v22
	v_mul_f32_e32 v14, v21, v14
	v_cvt_f32_f16_e32 v21, v23
	v_cvt_f32_f16_e32 v22, v15
	v_cvt_f32_f16_sdwa v23, v23 dst_sel:DWORD dst_unused:UNUSED_PAD src0_sel:WORD_1
	v_cvt_f32_f16_sdwa v15, v15 dst_sel:DWORD dst_unused:UNUSED_PAD src0_sel:WORD_1
	v_med3_f32 v20, v20, s62, v187
	v_med3_f32 v14, v14, s62, v187
	v_mul_f32_e32 v21, v0, v21
	v_cvt_pk_fp8_f32 v33, v20, v14
	v_mul_f32_e32 v21, v21, v22
	v_mul_f32_e32 v22, v1, v23
	v_mul_f32_e32 v15, v22, v15
	v_med3_f32 v14, v21, s62, v187
	v_med3_f32 v15, v15, s62, v187
	v_cvt_pk_fp8_f32 v33, v14, v15 op_sel:[0,0,1]
	v_lshl_add_u64 v[14:15], s[30:31], 0, v[24:25]
	ds_read_b128 v[20:23], v36
	v_lshl_add_u64 v[14:15], v[14:15], 0, v[138:139]
	s_waitcnt vmcnt(6)
	v_mov_b32_e32 v16, v240
	v_mov_b32_e32 v17, v241
	v_mov_b32_e32 v18, v242
	v_mov_b32_e32 v19, v243
	v_cvt_f32_f16_e32 v35, v16
	v_cvt_f32_f16_sdwa v16, v16 dst_sel:DWORD dst_unused:UNUSED_PAD src0_sel:WORD_1
	global_store_dwordx2 v[14:15], v[32:33], off offset:2048
	s_waitcnt lgkmcnt(0)
	v_cvt_f32_f16_e32 v34, v20
	v_cvt_f32_f16_sdwa v20, v20 dst_sel:DWORD dst_unused:UNUSED_PAD src0_sel:WORD_1
	v_cvt_f32_f16_e32 v32, v17
	v_cvt_f32_f16_sdwa v17, v17 dst_sel:DWORD dst_unused:UNUSED_PAD src0_sel:WORD_1
	v_mul_f32_e32 v14, v6, v34
	v_mul_f32_e32 v15, v7, v20
	v_cvt_f32_f16_e32 v20, v21
	v_cvt_f32_f16_sdwa v21, v21 dst_sel:DWORD dst_unused:UNUSED_PAD src0_sel:WORD_1
	v_mul_f32_e32 v14, v14, v35
	v_mul_f32_e32 v15, v15, v16
	v_mul_f32_e32 v16, v4, v20
	v_med3_f32 v14, v14, s62, v187
	v_med3_f32 v15, v15, s62, v187
	v_mov_b32_e32 v20, v139
	v_cvt_pk_fp8_f32 v20, v14, v15
	v_mul_f32_e32 v21, v5, v21
	v_mul_f32_e32 v16, v16, v32
	v_mul_f32_e32 v14, v21, v17
	v_med3_f32 v15, v16, s62, v187
	v_med3_f32 v14, v14, s62, v187
	v_cvt_pk_fp8_f32 v20, v15, v14 op_sel:[0,0,1]
	v_cvt_f32_f16_e32 v14, v22
	v_cvt_f32_f16_e32 v15, v18
	v_cvt_f32_f16_sdwa v16, v22 dst_sel:DWORD dst_unused:UNUSED_PAD src0_sel:WORD_1
	v_cvt_f32_f16_sdwa v17, v18 dst_sel:DWORD dst_unused:UNUSED_PAD src0_sel:WORD_1
	v_mul_f32_e32 v14, v2, v14
	v_mul_f32_e32 v14, v14, v15
	v_mul_f32_e32 v15, v3, v16
	v_cvt_f32_f16_e32 v16, v23
	v_mul_f32_e32 v15, v15, v17
	v_cvt_f32_f16_e32 v17, v19
	v_cvt_f32_f16_sdwa v18, v23 dst_sel:DWORD dst_unused:UNUSED_PAD src0_sel:WORD_1
	v_cvt_f32_f16_sdwa v19, v19 dst_sel:DWORD dst_unused:UNUSED_PAD src0_sel:WORD_1
	v_med3_f32 v14, v14, s62, v187
	v_med3_f32 v15, v15, s62, v187
	v_mov_b32_e32 v21, v139
	v_mul_f32_e32 v16, v0, v16
	v_cvt_pk_fp8_f32 v21, v14, v15
	v_mul_f32_e32 v16, v16, v17
	v_mul_f32_e32 v17, v1, v18
	v_mul_f32_e32 v18, v17, v19
	v_med3_f32 v19, v16, s62, v187
	ds_read_b128 v[14:17], v37
	v_med3_f32 v18, v18, s62, v187
	v_cvt_pk_fp8_f32 v21, v19, v18 op_sel:[0,0,1]
	v_lshl_add_u64 v[18:19], s[30:31], 0, v[28:29]
	v_lshl_add_u64 v[18:19], v[18:19], 0, v[138:139]
	s_waitcnt lgkmcnt(0)
	v_cvt_f32_f16_e32 v22, v14
	v_cvt_f32_f16_sdwa v14, v14 dst_sel:DWORD dst_unused:UNUSED_PAD src0_sel:WORD_1
	s_waitcnt vmcnt(6)
	v_mov_b32_e32 v10, v244
	v_mov_b32_e32 v11, v245
	v_mov_b32_e32 v12, v246
	v_mov_b32_e32 v13, v247
	v_cvt_f32_f16_e32 v23, v10
	global_store_dwordx2 v[18:19], v[20:21], off offset:2048
	v_cvt_f32_f16_sdwa v10, v10 dst_sel:DWORD dst_unused:UNUSED_PAD src0_sel:WORD_1
	v_cvt_f32_f16_e32 v19, v15
	v_cvt_f32_f16_e32 v20, v11
	v_mul_f32_e32 v18, v6, v22
	v_mul_f32_e32 v14, v7, v14
	v_cvt_f32_f16_sdwa v15, v15 dst_sel:DWORD dst_unused:UNUSED_PAD src0_sel:WORD_1
	v_mul_f32_e32 v18, v18, v23
	v_mul_f32_e32 v10, v14, v10
	v_mul_f32_e32 v14, v4, v19
	v_cvt_f32_f16_sdwa v11, v11 dst_sel:DWORD dst_unused:UNUSED_PAD src0_sel:WORD_1
	v_mul_f32_e32 v19, v14, v20
	v_med3_f32 v18, v18, s62, v187
	v_med3_f32 v10, v10, s62, v187
	v_mov_b32_e32 v14, v139
	v_cvt_pk_fp8_f32 v14, v18, v10
	v_mul_f32_e32 v15, v5, v15
	v_mul_f32_e32 v10, v15, v11
	v_med3_f32 v11, v19, s62, v187
	v_med3_f32 v10, v10, s62, v187
	v_cvt_pk_fp8_f32 v14, v11, v10 op_sel:[0,0,1]
	v_cvt_f32_f16_e32 v10, v16
	v_cvt_f32_f16_e32 v11, v12
	v_cvt_f32_f16_sdwa v15, v16 dst_sel:DWORD dst_unused:UNUSED_PAD src0_sel:WORD_1
	v_cvt_f32_f16_sdwa v12, v12 dst_sel:DWORD dst_unused:UNUSED_PAD src0_sel:WORD_1
	v_mul_f32_e32 v10, v2, v10
	v_mul_f32_e32 v10, v10, v11
	v_mul_f32_e32 v11, v3, v15
	v_mul_f32_e32 v11, v11, v12
	v_cvt_f32_f16_e32 v12, v17
	v_cvt_f32_f16_e32 v15, v13
	v_cvt_f32_f16_sdwa v16, v17 dst_sel:DWORD dst_unused:UNUSED_PAD src0_sel:WORD_1
	v_cvt_f32_f16_sdwa v13, v13 dst_sel:DWORD dst_unused:UNUSED_PAD src0_sel:WORD_1
	v_mul_f32_e32 v12, v0, v12
	v_mul_f32_e32 v12, v12, v15
	v_mul_f32_e32 v15, v1, v16
	v_mul_f32_e32 v16, v15, v13
	v_med3_f32 v10, v10, s62, v187
	v_med3_f32 v11, v11, s62, v187
	v_mov_b32_e32 v15, v139
	v_cvt_pk_fp8_f32 v15, v10, v11
	v_med3_f32 v17, v12, s62, v187
	ds_read_b128 v[10:13], v38
	s_waitcnt vmcnt(6)
	v_mov_b32_e32 v24, v248
	v_mov_b32_e32 v25, v249
	v_mov_b32_e32 v26, v250
	v_mov_b32_e32 v27, v251
	v_cvt_f32_f16_e32 v19, v24
	v_cvt_f32_f16_sdwa v20, v24 dst_sel:DWORD dst_unused:UNUSED_PAD src0_sel:WORD_1
	v_med3_f32 v16, v16, s62, v187
	v_cvt_pk_fp8_f32 v15, v17, v16 op_sel:[0,0,1]
	s_waitcnt lgkmcnt(0)
	v_cvt_f32_f16_e32 v18, v10
	v_cvt_f32_f16_sdwa v10, v10 dst_sel:DWORD dst_unused:UNUSED_PAD src0_sel:WORD_1
	v_lshl_add_u64 v[16:17], s[30:31], 0, v[30:31]
	v_lshl_add_u64 v[16:17], v[16:17], 0, v[138:139]
	v_mul_f32_e32 v6, v6, v18
	v_mul_f32_e32 v7, v7, v10
	v_cvt_f32_f16_e32 v10, v11
	v_cvt_f32_f16_e32 v18, v25
	v_cvt_f32_f16_sdwa v11, v11 dst_sel:DWORD dst_unused:UNUSED_PAD src0_sel:WORD_1
	v_mul_f32_e32 v6, v6, v19
	v_cvt_f32_f16_sdwa v19, v25 dst_sel:DWORD dst_unused:UNUSED_PAD src0_sel:WORD_1
	v_mul_f32_e32 v4, v4, v10
	v_mul_f32_e32 v7, v7, v20
	v_mul_f32_e32 v10, v4, v18
	v_mul_f32_e32 v4, v5, v11
	v_mul_f32_e32 v5, v4, v19
	v_med3_f32 v6, v6, s62, v187
	v_med3_f32 v7, v7, s62, v187
	v_mov_b32_e32 v4, v139
	v_cvt_pk_fp8_f32 v4, v6, v7
	v_cvt_f32_f16_e32 v7, v12
	v_med3_f32 v6, v10, s62, v187
	v_med3_f32 v5, v5, s62, v187
	v_cvt_f32_f16_e32 v10, v26
	v_cvt_f32_f16_sdwa v11, v12 dst_sel:DWORD dst_unused:UNUSED_PAD src0_sel:WORD_1
	v_cvt_pk_fp8_f32 v4, v6, v5 op_sel:[0,0,1]
	v_cvt_f32_f16_sdwa v5, v26 dst_sel:DWORD dst_unused:UNUSED_PAD src0_sel:WORD_1
	v_cvt_f32_f16_e32 v6, v13
	v_mul_f32_e32 v2, v2, v7
	v_mul_f32_e32 v2, v2, v10
	v_mul_f32_e32 v3, v3, v11
	v_cvt_f32_f16_sdwa v10, v13 dst_sel:DWORD dst_unused:UNUSED_PAD src0_sel:WORD_1
	v_cvt_f32_f16_e32 v7, v27
	v_mul_f32_e32 v3, v3, v5
	v_mul_f32_e32 v0, v0, v6
	v_cvt_f32_f16_sdwa v6, v27 dst_sel:DWORD dst_unused:UNUSED_PAD src0_sel:WORD_1
	v_med3_f32 v2, v2, s62, v187
	v_med3_f32 v3, v3, s62, v187
	v_mov_b32_e32 v5, v139
	v_cvt_pk_fp8_f32 v5, v2, v3
	v_mul_f32_e32 v1, v1, v10
	v_mul_f32_e32 v0, v0, v7
	v_mul_f32_e32 v1, v1, v6
	v_med3_f32 v0, v0, s62, v187
	v_med3_f32 v1, v1, s62, v187
	v_cvt_pk_fp8_f32 v5, v0, v1 op_sel:[0,0,1]
	v_lshl_add_u64 v[0:1], s[30:31], 0, v[8:9]
	v_lshl_add_u64 v[0:1], v[0:1], 0, v[138:139]
	global_store_dwordx2 v[16:17], v[14:15], off offset:2048
	global_store_dwordx2 v[0:1], v[4:5], off offset:2048
	s_cbranch_vccnz .LBB0_1610
